# attention interior loop: K fragment ds_reads issued before the LDS-DMA issue code
# speedup vs baseline: 1.0021x; 1.0021x over previous
.LBB0_104:
	s_mov_b32 s43, s13
	s_mul_i32 s52, s43, 0x3000
	s_add_i32 s52, s52, 16
	v_add_u32_e32 v52, s52, v149
	ds_read_b128 v[48:51], v52
	ds_read_b128 v[106:109], v52 offset:32
	ds_read_b128 v[64:67], v52 offset:6144
	ds_read_b128 v[110:113], v52 offset:6176
	ds_read_b128 v[114:117], v52 offset:64
	ds_read_b128 v[118:121], v52 offset:96
	ds_read_b128 v[122:125], v52 offset:6208
	ds_read_b128 v[126:129], v52 offset:6240
	v_add_u32_e32 v52, s52, v150
	ds_read_b128 v[132:135], v52
	ds_read_b128 v[160:163], v52 offset:6144
	v_add_u32_e32 v52, s52, v151
	ds_read_b128 v[164:167], v52
	ds_read_b128 v[168:171], v52 offset:6144
	s_add_i32 s4, s49, 2
	s_cmp_lt_u32 s4, s36
	s_cselect_b32 s4, s4, s48
	s_mul_i32 s14, s4, 0x3000
	s_mul_hi_u32 s15, s4, 0x3000
	s_add_u32 s14, s6, s14
	s_mul_i32 s52, s37, 0x3000
	s_addc_u32 s15, s7, s15
	s_add_i32 s52, s33, s52
	v_lshl_add_u64 v[172:173], v[144:145], 1, s[14:15]
	s_mov_b32 m0, s52
	s_andn2_b64 vcc, exec, s[10:11]
	global_load_lds_dwordx4 v[172:173], off
	s_cbranch_vccnz .LBB0_106
	v_lshl_add_u64 v[172:173], v[80:81], 1, s[14:15]
	s_add_i32 m0, s52, 0x2000
	s_nop 0
	global_load_lds_dwordx4 v[172:173], off
.LBB0_106:
	s_lshl_b64 s[14:15], s[4:5], 17
	s_lshl_b32 s4, s37, 13
	v_lshl_add_u64 v[172:173], v[146:147], 0, s[14:15]
	s_add_i32 s4, s33, s4
	v_lshl_add_u64 v[172:173], v[172:173], 0, s[20:21]
	s_add_i32 m0, s4, 0x9000
	global_load_lds_dwordx4 v[172:173], off
	s_waitcnt lgkmcnt(0)
	v_mfma_f32_32x32x16_bf16 v[48:63], v[48:51], v[82:85], 0
	v_mfma_f32_32x32x16_bf16 v[64:79], v[64:67], v[82:85], 0
	v_mfma_f32_32x32x16_bf16 v[48:63], v[106:109], v[86:89], v[48:63]
	v_mfma_f32_32x32x16_bf16 v[64:79], v[110:113], v[86:89], v[64:79]
	v_mfma_f32_32x32x16_bf16 v[48:63], v[114:117], v[90:93], v[48:63]
	v_mfma_f32_32x32x16_bf16 v[64:79], v[122:125], v[90:93], v[64:79]
	v_mfma_f32_32x32x16_bf16 v[48:63], v[118:121], v[94:97], v[48:63]
	v_mfma_f32_32x32x16_bf16 v[64:79], v[126:129], v[94:97], v[64:79]
	v_mfma_f32_32x32x16_bf16 v[48:63], v[132:135], v[98:101], v[48:63]
	v_mfma_f32_32x32x16_bf16 v[64:79], v[160:163], v[98:101], v[64:79]
	v_mfma_f32_32x32x16_bf16 v[48:63], v[164:167], v[102:105], v[48:63]
	v_mfma_f32_32x32x16_bf16 v[64:79], v[168:171], v[102:105], v[64:79]
	v_lshl_add_u32 v108, s43, 13, v131
	ds_read_b64_tr_b16 v[132:133], v108 offset:0
	ds_read_b64_tr_b16 v[134:135], v108 offset:1024
	ds_read_b64_tr_b16 v[160:161], v108 offset:64
	ds_read_b64_tr_b16 v[162:163], v108 offset:1088
	ds_read_b64_tr_b16 v[126:127], v108 offset:2048
	ds_read_b64_tr_b16 v[128:129], v108 offset:3072
	ds_read_b64_tr_b16 v[122:123], v108 offset:2112
	ds_read_b64_tr_b16 v[124:125], v108 offset:3136
	ds_read_b64_tr_b16 v[118:119], v108 offset:4096
	ds_read_b64_tr_b16 v[120:121], v108 offset:5120
	ds_read_b64_tr_b16 v[114:115], v108 offset:4160
	ds_read_b64_tr_b16 v[116:117], v108 offset:5184
	ds_read_b64_tr_b16 v[110:111], v108 offset:6144
	ds_read_b64_tr_b16 v[112:113], v108 offset:7168
	ds_read_b64_tr_b16 v[106:107], v108 offset:6208
	ds_read_b64_tr_b16 v[108:109], v108 offset:7232
	s_nop 8
	v_exp_f32_e32 v50, v50
	v_exp_f32_e32 v51, v51
	v_exp_f32_e32 v52, v52
	v_exp_f32_e32 v53, v53
	v_exp_f32_e32 v54, v54
	v_exp_f32_e32 v55, v55
	v_exp_f32_e32 v48, v48
	v_exp_f32_e32 v49, v49
	v_add_f32_e32 v32, v32, v50
	v_add_f32_e32 v33, v33, v51
	v_add_f32_e32 v34, v34, v52
	v_add_f32_e32 v35, v35, v53
	v_add_f32_e32 v32, v32, v54
	v_add_f32_e32 v33, v33, v55
	v_add_f32_e32 v34, v34, v48
	v_add_f32_e32 v35, v35, v49
	s_waitcnt lgkmcnt(0)
	v_cvt_pk_bf16_f32 v48, v48, v49
	v_cvt_pk_bf16_f32 v49, v50, v51
	v_cvt_pk_bf16_f32 v50, v52, v53
	v_cvt_pk_bf16_f32 v51, v54, v55
	s_nop 1
	v_mfma_f32_32x32x16_bf16 v[0:15], v[132:135], v[48:51], v[0:15]
	v_exp_f32_e32 v56, v56
	v_exp_f32_e32 v57, v57
	v_exp_f32_e32 v58, v58
	v_exp_f32_e32 v59, v59
	v_exp_f32_e32 v60, v60
	v_exp_f32_e32 v61, v61
	v_exp_f32_e32 v62, v62
	v_mfma_f32_32x32x16_bf16 v[16:31], v[160:163], v[48:51], v[16:31]
	v_exp_f32_e32 v63, v63
	v_exp_f32_e32 v64, v64
	v_exp_f32_e32 v65, v65
	v_exp_f32_e32 v66, v66
	v_exp_f32_e32 v67, v67
	v_exp_f32_e32 v68, v68
	v_exp_f32_e32 v69, v69
	v_add_f32_e32 v32, v32, v56
	v_add_f32_e32 v33, v33, v57
	v_add_f32_e32 v34, v34, v58
	v_add_f32_e32 v35, v35, v59
	v_add_f32_e32 v32, v32, v60
	v_add_f32_e32 v33, v33, v61
	v_add_f32_e32 v34, v34, v62
	v_add_f32_e32 v35, v35, v63
	v_cvt_pk_bf16_f32 v48, v56, v57
	v_cvt_pk_bf16_f32 v49, v58, v59
	v_cvt_pk_bf16_f32 v50, v60, v61
	v_cvt_pk_bf16_f32 v51, v62, v63
	v_exp_f32_e32 v70, v70
	v_exp_f32_e32 v71, v71
	v_exp_f32_e32 v72, v72
	v_mfma_f32_32x32x16_bf16 v[0:15], v[126:129], v[48:51], v[0:15]
	v_exp_f32_e32 v73, v73
	v_exp_f32_e32 v74, v74
	v_exp_f32_e32 v75, v75
	v_exp_f32_e32 v76, v76
	v_exp_f32_e32 v77, v77
	v_exp_f32_e32 v78, v78
	v_exp_f32_e32 v79, v79
	v_mfma_f32_32x32x16_bf16 v[16:31], v[122:125], v[48:51], v[16:31]
	s_mov_b64 s[14:15], -1
	s_and_b64 vcc, exec, s[40:41]
	v_add_f32_e32 v32, v32, v64
	v_add_f32_e32 v33, v33, v65
	v_add_f32_e32 v34, v34, v66
	v_add_f32_e32 v35, v35, v67
	v_add_f32_e32 v32, v32, v68
	v_add_f32_e32 v33, v33, v69
	v_add_f32_e32 v34, v34, v70
	v_add_f32_e32 v35, v35, v71
	v_cvt_pk_bf16_f32 v48, v64, v65
	v_cvt_pk_bf16_f32 v49, v66, v67
	v_cvt_pk_bf16_f32 v50, v68, v69
	v_cvt_pk_bf16_f32 v51, v70, v71
	s_nop 0
	v_mfma_f32_32x32x16_bf16 v[0:15], v[118:121], v[48:51], v[0:15]
	v_mfma_f32_32x32x16_bf16 v[16:31], v[114:117], v[48:51], v[16:31]
	v_add_f32_e32 v32, v32, v72
	v_add_f32_e32 v33, v33, v73
	v_add_f32_e32 v34, v34, v74
	v_add_f32_e32 v35, v35, v75
	v_add_f32_e32 v32, v32, v76
	v_add_f32_e32 v33, v33, v77
	v_add_f32_e32 v34, v34, v78
	v_add_f32_e32 v35, v35, v79
	v_cvt_pk_bf16_f32 v48, v72, v73
	v_cvt_pk_bf16_f32 v49, v74, v75
	v_cvt_pk_bf16_f32 v50, v76, v77
	v_cvt_pk_bf16_f32 v51, v78, v79
	s_nop 0
	v_mfma_f32_32x32x16_bf16 v[0:15], v[110:113], v[48:51], v[0:15]
	v_mfma_f32_32x32x16_bf16 v[16:31], v[106:109], v[48:51], v[16:31]
	s_cbranch_vccz .LBB0_108
	s_waitcnt vmcnt(2)
	s_mov_b64 s[14:15], 0
